# v104 + every workgroup's first item of a mix step comes from the second queue (the 256 short gating/conv items, one each); FoX-first workgroups use the FoX queue from their second item on
# speedup vs baseline: 1.0026x; 1.0026x over previous
;     ...
;     auto fetch = [&]() -> int {
;         auto q1 = [&](int i) -> int { return i < N_A + N_C ? N_D + N_B + i : N_D + (i - (N_A + N_C)); };
;         if (pref == 0) { int i = (int)atomicAdd(ctr, 1u); if (i < N_D) return i; i = (int)atomicAdd(ctr + 32, 1u); return i < N_ALL - N_D ? q1(i) : N_ALL; }
;         int i = (int)atomicAdd(ctr + 32, 1u); if (i < N_ALL - N_D) return q1(i); i = (int)atomicAdd(ctr, 1u); return i < N_D ? i : N_ALL; };
;     int nxt = 0;
;     if (threadIdx.x == 0) nxt = fetch();
.LBB0_112:
	v_readlane_b32 s0, v253, 49
	v_readlane_b32 s1, v253, 50
	s_lshl_b32 s0, s0, 1
	v_readlane_b32 s1, v253, 51
	s_add_i32 s0, s0, s1
	s_ashr_i32 s1, s0, 31
	v_readlane_b32 s20, v251, 1
	s_lshl_b64 s[0:1], s[0:1], 2
	v_readlane_b32 s22, v251, 3
	v_readlane_b32 s23, v251, 4
	s_add_u32 s0, s22, s0
	s_addc_u32 s1, s23, s1
	v_writelane_b32 v253, s0, 55
	v_mov_b32_e32 v180, 0
	v_readlane_b32 s21, v251, 2
	v_writelane_b32 v253, s1, 56
	s_getreg_b32 s0, hwreg(HW_REG_XCC_ID, 0, 4)
	s_lshr_b32 s0, 0x49, s0
	s_and_b32 s0, s0, 1
	s_cmp_eq_u32 s0, 0
	s_cselect_b64 s[0:1], -1, 0
	v_writelane_b32 v253, s0, 57
	v_readlane_b32 s24, v251, 5
	v_readlane_b32 s25, v251, 6
	v_writelane_b32 v253, s1, 58
	v_readlane_b32 s26, v251, 7
	v_readlane_b32 s27, v251, 8
	s_mov_b64 s[0:1], exec
	v_readlane_b32 s20, v251, 13
	v_readlane_b32 s21, v251, 14
	s_and_b64 s[20:21], s[0:1], s[20:21]
	s_mov_b64 exec, s[20:21]
	s_cbranch_execz .LBB0_131
	v_readlane_b32 s20, v253, 57
	v_readlane_b32 s21, v253, 58
	s_and_b64 vcc, exec, s[20:21]
	s_mov_b64 s[22:23], exec
	v_mbcnt_lo_u32_b32 v0, s22, 0
	v_mbcnt_hi_u32_b32 v0, s23, v0
	v_cmp_eq_u32_e32 vcc, 0, v0
	s_and_saveexec_b64 s[20:21], vcc
	s_cbranch_execz .LBB0_116
	s_bcnt1_i32_b64 s22, s[22:23]
	v_mov_b32_e32 v2, s22
	v_readlane_b32 s22, v253, 55
	v_readlane_b32 s23, v253, 56
	s_nop 4
	global_atomic_add v2, v1, v2, s[22:23] offset:128 sc0
